# opt1: fast path (no causal mask, v_max3) for non-diagonal selected blocks in NSA selected branch
# speedup vs baseline: 1.0279x; 1.0279x over previous
; __device__ __forceinline__ float shx(float v, int m) { return __shfl_xor(v, m); }
; template <class KB>
; __device__ __forceinline__ void sel_run(int nit, KB kbof, const half8 (&qf)[2][2], const unsigned char* kf, const unsigned char* vf, const int (&tqs)[2], int qq,
;                                         f32x4 (&o)[2][4], float (&m)[2], float (&l)[2], int g) {
;     ...
;         half8 vh[8];
; #pragma unroll
;         for (int i = 0; i < 8; ++i) vh[i] = fp8x8_to_half8(va[i]);
;         {
;             const unsigned char* vp = vf + (size_t)(kbN >> 5) * 2048;
; #pragma unroll
;             for (int i = 0; i < 8; ++i) va[i] = *(const u32x2*)(vp + i * 512);
;         }
; #pragma unroll
;         for (int s_ = 0; s_ < 2; ++s_)
;             if (need[s_]) {
;                 float p[4][4]; float mx = -1e30f;
;                 const int klim = selq[s_] ? tqs[s_] - kbA - 4 * g : -1;
; #pragma unroll
;                 for (int t = 0; t < 4; ++t)
; #pragma unroll
;                     for (int r = 0; r < 4; ++r) { if (16 * t + r <= klim) mx = fmaxf(mx, s[s_][t][r]); }
;                 if (__ballot(mx > m[s_] + RESC_THR) != 0ull) {
;                     mx = fmaxf(mx, shx(mx, 16)); mx = fmaxf(mx, shx(mx, 32));
;                     const float mn = fmaxf(m[s_], mx); const float corr = __builtin_amdgcn_exp2f(m[s_] - mn); m[s_] = mn;
;                     l[s_] = l[s_] * corr;
; #pragma unroll
;                     for (int dt = 0; dt < 4; ++dt) o[s_][dt] = o[s_][dt] * corr;
;                 }
.LBB0_934:
	v_cvt_scalef32_pk_f16_fp8 v90, v122, 1.0
	v_cvt_scalef32_pk_f16_fp8 v91, v122, 1.0 op_sel:[1,0,0]
	v_cvt_scalef32_pk_f16_fp8 v92, v123, 1.0
	v_cvt_scalef32_pk_f16_fp8 v93, v123, 1.0 op_sel:[1,0,0]
	v_lshl_add_u64 v[122:123], v[120:121], 0, s[84:85]
	v_cvt_scalef32_pk_f16_fp8 v102, v188, 1.0
	v_cvt_scalef32_pk_f16_fp8 v103, v188, 1.0 op_sel:[1,0,0]
	v_cvt_scalef32_pk_f16_fp8 v104, v189, 1.0
	v_cvt_scalef32_pk_f16_fp8 v105, v189, 1.0 op_sel:[1,0,0]
	v_cvt_scalef32_pk_f16_fp8 v94, v186, 1.0
	v_cvt_scalef32_pk_f16_fp8 v95, v186, 1.0 op_sel:[1,0,0]
	v_cvt_scalef32_pk_f16_fp8 v96, v187, 1.0
	v_cvt_scalef32_pk_f16_fp8 v97, v187, 1.0 op_sel:[1,0,0]
	v_cvt_scalef32_pk_f16_fp8 v86, v184, 1.0
	v_cvt_scalef32_pk_f16_fp8 v87, v184, 1.0 op_sel:[1,0,0]
	v_cvt_scalef32_pk_f16_fp8 v88, v185, 1.0
	v_cvt_scalef32_pk_f16_fp8 v89, v185, 1.0 op_sel:[1,0,0]
	v_cvt_scalef32_pk_f16_fp8 v82, v180, 1.0
	v_cvt_scalef32_pk_f16_fp8 v83, v180, 1.0 op_sel:[1,0,0]
	v_cvt_scalef32_pk_f16_fp8 v84, v181, 1.0
	v_cvt_scalef32_pk_f16_fp8 v85, v181, 1.0 op_sel:[1,0,0]
	v_cvt_scalef32_pk_f16_fp8 v110, v158, 1.0
	v_cvt_scalef32_pk_f16_fp8 v111, v158, 1.0 op_sel:[1,0,0]
	v_cvt_scalef32_pk_f16_fp8 v112, v159, 1.0
	v_cvt_scalef32_pk_f16_fp8 v113, v159, 1.0 op_sel:[1,0,0]
	v_cvt_scalef32_pk_f16_fp8 v106, v156, 1.0
	v_cvt_scalef32_pk_f16_fp8 v107, v156, 1.0 op_sel:[1,0,0]
	v_cvt_scalef32_pk_f16_fp8 v108, v157, 1.0
	v_cvt_scalef32_pk_f16_fp8 v109, v157, 1.0 op_sel:[1,0,0]
	v_cvt_scalef32_pk_f16_fp8 v98, v126, 1.0
	v_cvt_scalef32_pk_f16_fp8 v99, v126, 1.0 op_sel:[1,0,0]
	v_cvt_scalef32_pk_f16_fp8 v100, v127, 1.0
	v_cvt_scalef32_pk_f16_fp8 v101, v127, 1.0 op_sel:[1,0,0]
	flat_load_dwordx2 v[188:189], v[122:123]
	flat_load_dwordx2 v[186:187], v[122:123] offset:512
	flat_load_dwordx2 v[184:185], v[122:123] offset:1024
	flat_load_dwordx2 v[180:181], v[122:123] offset:1536
	flat_load_dwordx2 v[158:159], v[122:123] offset:2048
	flat_load_dwordx2 v[156:157], v[122:123] offset:2560
	flat_load_dwordx2 v[126:127], v[122:123] offset:3072
	s_nop 0
	flat_load_dwordx2 v[122:123], v[122:123] offset:3584
	s_add_i32 s100, s12, 64
	s_lshr_b32 s33, s13, 8
	s_andn2_b64 vcc, exec, s[10:11]
	v_subrev_u32_e32 v226, s12, v213
	s_cbranch_vccnz .LBB0_938
	s_cmp_le_u32 s100, s93
	s_cbranch_scc1 .Lsel_fast0
	v_lshrrev_b32_e64 v227, v192, s33
	v_and_b32_e32 v227, 1, v227
	v_add_u32_e32 v228, v226, v223
	v_cmp_eq_u32_e32 vcc, 1, v227
	v_max_f32_e32 v229, v55, v55
	v_max_f32_e32 v230, v63, v63
	v_cndmask_b32_e32 v227, -1, v228, vcc
	v_max_f32_e32 v228, v54, v54
	v_max_f32_e32 v228, 0xf149f2ca, v228
	v_cmp_gt_i32_e64 s[42:43], 0, v227
	v_cmp_gt_i32_e64 s[40:41], 1, v227
	v_cmp_gt_i32_e64 s[38:39], 2, v227
	v_cndmask_b32_e64 v228, v228, v172, s[42:43]
	v_max_f32_e32 v229, v228, v229
	v_cndmask_b32_e64 v228, v229, v228, s[40:41]
	v_max_f32_e32 v229, v56, v56
	v_max_f32_e32 v229, v228, v229
	v_cndmask_b32_e64 v228, v229, v228, s[38:39]
	v_max_f32_e32 v229, v57, v57
	v_max_f32_e32 v229, v228, v229
	v_cmp_gt_i32_e64 s[36:37], 3, v227
	v_cmp_gt_i32_e64 s[34:35], 16, v227
	v_cmp_gt_i32_e64 s[30:31], 17, v227
	v_cndmask_b32_e64 v228, v229, v228, s[36:37]
	v_max_f32_e32 v229, v62, v62
	v_max_f32_e32 v229, v228, v229
	v_cndmask_b32_e64 v228, v229, v228, s[34:35]
	v_max_f32_e32 v229, v228, v228
	v_max_f32_e32 v229, v229, v230
	v_cndmask_b32_e64 v228, v229, v228, s[30:31]
	v_max_f32_e32 v229, v228, v228
	v_max_f32_e32 v230, v64, v64
	v_max_f32_e32 v229, v229, v230
	v_cmp_gt_i32_e64 s[28:29], 18, v227
	v_max_f32_e32 v230, v65, v65
	v_cmp_gt_i32_e64 s[26:27], 19, v227
	v_cndmask_b32_e64 v228, v229, v228, s[28:29]
	v_max_f32_e32 v229, v228, v228
	v_max_f32_e32 v229, v229, v230
	v_cndmask_b32_e64 v228, v229, v228, s[26:27]
	v_max_f32_e32 v229, v228, v228
	v_max_f32_e32 v230, v70, v70
	v_max_f32_e32 v229, v229, v230
	v_cmp_gt_i32_e64 s[24:25], 32, v227
	v_max_f32_e32 v230, v71, v71
	v_cmp_gt_i32_e64 s[22:23], 33, v227
	v_cndmask_b32_e64 v228, v229, v228, s[24:25]
	v_max_f32_e32 v229, v228, v228
	v_max_f32_e32 v229, v229, v230
	v_cndmask_b32_e64 v228, v229, v228, s[22:23]
	v_max_f32_e32 v229, v228, v228
	v_max_f32_e32 v230, v72, v72
	v_max_f32_e32 v229, v229, v230
	v_cmp_gt_i32_e64 s[20:21], 34, v227
	v_max_f32_e32 v230, v73, v73
	v_cmp_gt_i32_e64 s[18:19], 35, v227
	v_cndmask_b32_e64 v228, v229, v228, s[20:21]
	v_max_f32_e32 v229, v228, v228
	v_max_f32_e32 v229, v229, v230
	v_cndmask_b32_e64 v228, v229, v228, s[18:19]
	v_max_f32_e32 v229, v228, v228
	v_max_f32_e32 v230, v78, v78
	v_max_f32_e32 v229, v229, v230
	v_cmp_gt_i32_e64 s[16:17], 48, v227
	v_max_f32_e32 v230, v79, v79
	v_cmp_gt_i32_e64 s[14:15], 49, v227
	v_cndmask_b32_e64 v228, v229, v228, s[16:17]
	v_max_f32_e32 v229, v228, v228
	v_max_f32_e32 v229, v229, v230
	v_cndmask_b32_e64 v228, v229, v228, s[14:15]
	v_max_f32_e32 v229, v228, v228
	v_max_f32_e32 v230, v80, v80
	v_max_f32_e32 v229, v229, v230
	v_cmp_gt_i32_e64 s[12:13], 50, v227
	v_max_f32_e32 v230, v81, v81
	v_cmp_gt_i32_e64 s[10:11], 51, v227
	v_cndmask_b32_e64 v228, v229, v228, s[12:13]
	v_max_f32_e32 v229, v228, v228
	v_max_f32_e32 v229, v229, v230
	v_cndmask_b32_e64 v227, v229, v228, s[10:11]
	v_add_f32_e32 v228, 0x41400000, v225
	v_cmp_gt_f32_e32 vcc, v227, v228
	s_cbranch_vccz .LBB0_937
	ds_bpermute_b32 v228, v173, v227
	v_max_f32_e32 v227, v227, v227
	s_waitcnt lgkmcnt(0)
	v_max_f32_e32 v228, v228, v228
	v_max_f32_e32 v227, v227, v228
	ds_bpermute_b32 v228, v222, v227
	s_waitcnt lgkmcnt(0)
	v_max3_f32 v227, v225, v227, v228
	v_sub_f32_e32 v225, v225, v227
	v_exp_f32_e32 v228, v225
	v_mov_b32_e32 v225, v227
	v_mul_f32_e32 v149, v149, v228
	v_pk_mul_f32 v[28:29], v[28:29], v[228:229] op_sel_hi:[1,0]
	v_pk_mul_f32 v[26:27], v[26:27], v[228:229] op_sel_hi:[1,0]
	v_pk_mul_f32 v[32:33], v[32:33], v[228:229] op_sel_hi:[1,0]
	v_pk_mul_f32 v[30:31], v[30:31], v[228:229] op_sel_hi:[1,0]
	v_pk_mul_f32 v[24:25], v[24:25], v[228:229] op_sel_hi:[1,0]
	v_pk_mul_f32 v[22:23], v[22:23], v[228:229] op_sel_hi:[1,0]
	v_pk_mul_f32 v[20:21], v[20:21], v[228:229] op_sel_hi:[1,0]
	v_pk_mul_f32 v[18:19], v[18:19], v[228:229] op_sel_hi:[1,0]

; __device__ __forceinline__ float shx(float v, int m) { return __shfl_xor(v, m); }
; template <class KB>
; __device__ __forceinline__ void sel_run(int nit, KB kbof, const half8 (&qf)[2][2], const unsigned char* kf, const unsigned char* vf, const int (&tqs)[2], int qq,
;                                         f32x4 (&o)[2][4], float (&m)[2], float (&l)[2], int g) {
;     ...
;         for (int s_ = 0; s_ < 2; ++s_)
;             if (need[s_]) {
;                 float p[4][4]; float mx = -1e30f;
;                 const int klim = selq[s_] ? tqs[s_] - kbA - 4 * g : -1;
; #pragma unroll
;                 for (int t = 0; t < 4; ++t)
; #pragma unroll
;                     for (int r = 0; r < 4; ++r) { if (16 * t + r <= klim) mx = fmaxf(mx, s[s_][t][r]); }
;                 if (__ballot(mx > m[s_] + RESC_THR) != 0ull) {
;                     mx = fmaxf(mx, shx(mx, 16)); mx = fmaxf(mx, shx(mx, 32));
;                     const float mn = fmaxf(m[s_], mx); const float corr = __builtin_amdgcn_exp2f(m[s_] - mn); m[s_] = mn;
;                     l[s_] = l[s_] * corr;
; #pragma unroll
;                     for (int dt = 0; dt < 4; ++dt) o[s_][dt] = o[s_][dt] * corr;
;                 }
.LBB0_938:
	s_andn2_b64 vcc, exec, s[2:3]
	s_cbranch_vccnz .LBB0_942
	s_cmp_le_u32 s100, s93
	s_cbranch_scc1 .Lsel_fast1
	v_lshrrev_b32_e64 v227, v214, s33
	v_and_b32_e32 v227, 1, v227
	v_add_u32_e32 v226, v226, v224
	v_cmp_eq_u32_e32 vcc, 1, v227
	v_max_f32_e32 v227, v50, v50
	v_max_f32_e32 v227, 0xf149f2ca, v227
	v_cndmask_b32_e32 v226, -1, v226, vcc
	v_cmp_gt_i32_e64 s[42:43], 0, v226
	v_max_f32_e32 v228, v51, v51
	v_cmp_gt_i32_e64 s[40:41], 1, v226
	v_cndmask_b32_e64 v227, v227, v172, s[42:43]
	v_max_f32_e32 v228, v227, v228
	v_cndmask_b32_e64 v227, v228, v227, s[40:41]
	v_max_f32_e32 v228, v52, v52
	v_max_f32_e32 v228, v227, v228
	v_cmp_gt_i32_e64 s[38:39], 2, v226
	v_cmp_gt_i32_e64 s[36:37], 3, v226
	v_cmp_gt_i32_e64 s[34:35], 16, v226
	v_cndmask_b32_e64 v227, v228, v227, s[38:39]
	v_max_f32_e32 v228, v53, v53
	v_max_f32_e32 v228, v227, v228
	v_cndmask_b32_e64 v227, v228, v227, s[36:37]
	v_max_f32_e32 v228, v58, v58
	v_max_f32_e32 v228, v227, v228
	v_cndmask_b32_e64 v227, v228, v227, s[34:35]
	v_max_f32_e32 v228, v227, v227
	v_max_f32_e32 v229, v59, v59
	v_max_f32_e32 v228, v228, v229
	v_cmp_gt_i32_e64 s[30:31], 17, v226
	v_max_f32_e32 v229, v60, v60
	v_cmp_gt_i32_e64 s[28:29], 18, v226
	v_cndmask_b32_e64 v227, v228, v227, s[30:31]
	v_max_f32_e32 v228, v227, v227
	v_max_f32_e32 v228, v228, v229
	v_cndmask_b32_e64 v227, v228, v227, s[28:29]
	v_max_f32_e32 v228, v227, v227
	v_max_f32_e32 v229, v61, v61
	v_max_f32_e32 v228, v228, v229
	v_cmp_gt_i32_e64 s[26:27], 19, v226
	v_max_f32_e32 v229, v66, v66
	v_cmp_gt_i32_e64 s[24:25], 32, v226
	v_cndmask_b32_e64 v227, v228, v227, s[26:27]
	v_max_f32_e32 v228, v227, v227
	v_max_f32_e32 v228, v228, v229
	v_cndmask_b32_e64 v227, v228, v227, s[24:25]
	v_max_f32_e32 v228, v227, v227
	v_max_f32_e32 v229, v67, v67
	v_max_f32_e32 v228, v228, v229
	v_cmp_gt_i32_e64 s[22:23], 33, v226
	v_max_f32_e32 v229, v68, v68
	v_cmp_gt_i32_e64 s[20:21], 34, v226
	v_cndmask_b32_e64 v227, v228, v227, s[22:23]
	v_max_f32_e32 v228, v227, v227
	v_max_f32_e32 v228, v228, v229
	v_cndmask_b32_e64 v227, v228, v227, s[20:21]
	v_max_f32_e32 v228, v227, v227
	v_max_f32_e32 v229, v69, v69
	v_max_f32_e32 v228, v228, v229
	v_cmp_gt_i32_e64 s[18:19], 35, v226
	v_max_f32_e32 v229, v74, v74
	v_cmp_gt_i32_e64 s[16:17], 48, v226
	v_cndmask_b32_e64 v227, v228, v227, s[18:19]
	v_max_f32_e32 v228, v227, v227
	v_max_f32_e32 v228, v228, v229
	v_cndmask_b32_e64 v227, v228, v227, s[16:17]
	v_max_f32_e32 v228, v227, v227
	v_max_f32_e32 v229, v75, v75
	v_max_f32_e32 v228, v228, v229
	v_cmp_gt_i32_e64 s[14:15], 49, v226
	v_max_f32_e32 v229, v76, v76
	v_cmp_gt_i32_e64 s[12:13], 50, v226
	v_cndmask_b32_e64 v227, v228, v227, s[14:15]
	v_max_f32_e32 v228, v227, v227
	v_max_f32_e32 v228, v228, v229
	v_cndmask_b32_e64 v227, v228, v227, s[12:13]
	v_max_f32_e32 v228, v227, v227
	v_max_f32_e32 v229, v77, v77
	v_max_f32_e32 v228, v228, v229
	v_cmp_gt_i32_e64 s[10:11], 51, v226
	s_nop 1
	v_cndmask_b32_e64 v226, v228, v227, s[10:11]
	v_add_f32_e32 v227, 0x41400000, v151
	v_cmp_gt_f32_e32 vcc, v226, v227
	s_cbranch_vccz .LBB0_941
	ds_bpermute_b32 v227, v173, v226
	v_max_f32_e32 v226, v226, v226
	s_waitcnt lgkmcnt(0)
	v_max_f32_e32 v227, v227, v227
	v_max_f32_e32 v226, v226, v227
	ds_bpermute_b32 v227, v222, v226
	s_waitcnt lgkmcnt(0)
	v_max3_f32 v227, v151, v226, v227
	v_sub_f32_e32 v151, v151, v227
	v_exp_f32_e32 v226, v151
	v_mov_b32_e32 v151, v227
	v_mul_f32_e32 v147, v147, v226
	v_pk_mul_f32 v[16:17], v[16:17], v[226:227] op_sel_hi:[1,0]
	v_pk_mul_f32 v[14:15], v[14:15], v[226:227] op_sel_hi:[1,0]
	v_pk_mul_f32 v[12:13], v[12:13], v[226:227] op_sel_hi:[1,0]
	v_pk_mul_f32 v[10:11], v[10:11], v[226:227] op_sel_hi:[1,0]
	v_pk_mul_f32 v[8:9], v[8:9], v[226:227] op_sel_hi:[1,0]
	v_pk_mul_f32 v[6:7], v[6:7], v[226:227] op_sel_hi:[1,0]
	v_pk_mul_f32 v[4:5], v[4:5], v[226:227] op_sel_hi:[1,0]
	v_pk_mul_f32 v[2:3], v[2:3], v[226:227] op_sel_hi:[1,0]

; #define MFMA16(a, b, c) __builtin_amdgcn_mfma_f32_16x16x32_f16((a), (b), (c), 0, 0, 0)
; __device__ __forceinline__ float shx(float v, int m) { return __shfl_xor(v, m); }
; template <class KB>
; __device__ __forceinline__ void sel_run(int nit, KB kbof, const half8 (&qf)[2][2], const unsigned char* kf, const unsigned char* vf, const int (&tqs)[2], int qq,
;                                         f32x4 (&o)[2][4], float (&m)[2], float (&l)[2], int g) {
;     ...
; #pragma unroll
;         for (int s_ = 0; s_ < 2; ++s_)
;             if (need[s_]) {
;                 float p[4][4]; float mx = -1e30f;
;                 const int klim = selq[s_] ? tqs[s_] - kbA - 4 * g : -1;
; #pragma unroll
;                 for (int t = 0; t < 4; ++t)
; #pragma unroll
;                     for (int r = 0; r < 4; ++r) { if (16 * t + r <= klim) mx = fmaxf(mx, s[s_][t][r]); }
;                 if (__ballot(mx > m[s_] + RESC_THR) != 0ull) {
;                     mx = fmaxf(mx, shx(mx, 16)); mx = fmaxf(mx, shx(mx, 32));
;                     const float mn = fmaxf(m[s_], mx); const float corr = __builtin_amdgcn_exp2f(m[s_] - mn); m[s_] = mn;
;                     l[s_] = l[s_] * corr;
; #pragma unroll
;                     for (int dt = 0; dt < 4; ++dt) o[s_][dt] = o[s_][dt] * corr;
;                 }
;                 float ps = 0.f;
; #pragma unroll
;                 for (int t = 0; t < 4; ++t)
; #pragma unroll
;                     for (int r = 0; r < 4; ++r) { p[t][r] = (16 * t + r <= klim) ? __builtin_amdgcn_exp2f(s[s_][t][r] - m[s_]) : 0.f; ps += p[t][r]; }
;                 l[s_] = l[s_] + ps;
;                 const half8 pfA = {(half_t)p[0][0], (half_t)p[0][1], (half_t)p[0][2], (half_t)p[0][3], (half_t)p[1][0], (half_t)p[1][1], (half_t)p[1][2], (half_t)p[1][3]};
;                 const half8 pfB = {(half_t)p[2][0], (half_t)p[2][1], (half_t)p[2][2], (half_t)p[2][3], (half_t)p[3][0], (half_t)p[3][1], (half_t)p[3][2], (half_t)p[3][3]};
; #pragma unroll
;                 for (int dt = 0; dt < 4; ++dt) { o[s_][dt] = MFMA16(vh[dt], pfA, o[s_][dt]); o[s_][dt] = MFMA16(vh[4 + dt], pfB, o[s_][dt]); }
.Lsel_fast0:
	v_lshrrev_b32_e64 v227, v192, s33
	v_max3_f32 v228, v54, v55, v56
	v_and_b32_e32 v227, 1, v227
	v_max3_f32 v229, v57, v62, v63
	v_cmp_eq_u32_e64 s[10:11], 1, v227
	v_max3_f32 v230, v64, v65, v70
	v_max3_f32 v231, v71, v72, v73
	v_max3_f32 v228, v228, v78, v79
	v_max3_f32 v229, v229, v80, v81
	v_add_f32_e32 v232, 0x41400000, v225
	v_max3_f32 v228, v228, v230, v231
	v_max_f32_e32 v228, v228, v229
	v_cndmask_b32_e64 v227, v172, v228, s[10:11]
	v_cmp_gt_f32_e32 vcc, v227, v232
	s_cbranch_vccz .Lsel_fast0_go
	ds_bpermute_b32 v228, v173, v227
	v_max_f32_e32 v227, v227, v227
	s_waitcnt lgkmcnt(0)
	v_max_f32_e32 v228, v228, v228
	v_max_f32_e32 v227, v227, v228
	ds_bpermute_b32 v228, v222, v227
	s_waitcnt lgkmcnt(0)
	v_max3_f32 v227, v225, v227, v228
	v_sub_f32_e32 v225, v225, v227
	v_exp_f32_e32 v228, v225
	v_mov_b32_e32 v225, v227
	v_mul_f32_e32 v149, v149, v228
	v_pk_mul_f32 v[26:27], v[26:27], v[228:229] op_sel_hi:[1,0]
	v_pk_mul_f32 v[28:29], v[28:29], v[228:229] op_sel_hi:[1,0]
	v_pk_mul_f32 v[30:31], v[30:31], v[228:229] op_sel_hi:[1,0]
	v_pk_mul_f32 v[32:33], v[32:33], v[228:229] op_sel_hi:[1,0]
	v_pk_mul_f32 v[22:23], v[22:23], v[228:229] op_sel_hi:[1,0]
	v_pk_mul_f32 v[24:25], v[24:25], v[228:229] op_sel_hi:[1,0]
	v_pk_mul_f32 v[18:19], v[18:19], v[228:229] op_sel_hi:[1,0]
	v_pk_mul_f32 v[20:21], v[20:21], v[228:229] op_sel_hi:[1,0]
.Lsel_fast0_go:
	v_cndmask_b32_e64 v227, -v172, v225, s[10:11]
	v_sub_f32_e32 v228, v54, v227
	v_sub_f32_e32 v229, v55, v227
	v_sub_f32_e32 v230, v56, v227
	v_sub_f32_e32 v231, v57, v227
	v_sub_f32_e32 v232, v62, v227
	v_sub_f32_e32 v233, v63, v227
	v_sub_f32_e32 v234, v64, v227
	v_sub_f32_e32 v235, v65, v227
	v_sub_f32_e32 v236, v70, v227
	v_sub_f32_e32 v237, v71, v227
	v_sub_f32_e32 v238, v72, v227
	v_sub_f32_e32 v239, v73, v227
	v_sub_f32_e32 v240, v78, v227
	v_sub_f32_e32 v241, v79, v227
	v_sub_f32_e32 v242, v80, v227
	v_sub_f32_e32 v243, v81, v227
	v_exp_f32_e32 v228, v228
	v_exp_f32_e32 v229, v229
	v_exp_f32_e32 v230, v230
	v_exp_f32_e32 v231, v231
	v_exp_f32_e32 v232, v232
	v_exp_f32_e32 v233, v233
	v_exp_f32_e32 v234, v234
	v_exp_f32_e32 v235, v235
	v_exp_f32_e32 v236, v236
	v_exp_f32_e32 v237, v237
	v_exp_f32_e32 v238, v238
	v_exp_f32_e32 v239, v239
	v_exp_f32_e32 v240, v240
	v_exp_f32_e32 v241, v241
	v_exp_f32_e32 v242, v242
	v_exp_f32_e32 v243, v243
	v_add_f32_e32 v149, v149, v228
	v_add_f32_e32 v227, v229, v230
	v_add_f32_e32 v149, v149, v231
	v_add_f32_e32 v227, v227, v232
	v_add_f32_e32 v149, v149, v233
	v_add_f32_e32 v227, v227, v234
	v_add_f32_e32 v149, v149, v235
	v_add_f32_e32 v227, v227, v236
	v_add_f32_e32 v149, v149, v237
	v_add_f32_e32 v227, v227, v238
	v_add_f32_e32 v149, v149, v239
	v_add_f32_e32 v227, v227, v240
	v_add_f32_e32 v149, v149, v241
	v_add_f32_e32 v227, v227, v242
	v_add_f32_e32 v149, v149, v243
	v_add_f32_e32 v149, v149, v227
	v_cvt_pk_f16_f32 v228, v228, v229
	v_cvt_pk_f16_f32 v229, v230, v231
	v_cvt_pk_f16_f32 v230, v232, v233
	v_cvt_pk_f16_f32 v231, v234, v235
	v_cvt_pk_f16_f32 v232, v236, v237
	v_cvt_pk_f16_f32 v233, v238, v239
	v_cvt_pk_f16_f32 v234, v240, v241
	v_cvt_pk_f16_f32 v235, v242, v243
	v_mfma_f32_16x16x32_f16 v[26:29], v[102:105], v[228:231], v[26:29]
	v_mfma_f32_16x16x32_f16 v[30:33], v[94:97], v[228:231], v[30:33]
	v_mfma_f32_16x16x32_f16 v[22:25], v[86:89], v[228:231], v[22:25]
	v_mfma_f32_16x16x32_f16 v[18:21], v[82:85], v[228:231], v[18:21]
	v_mfma_f32_16x16x32_f16 v[26:29], v[110:113], v[232:235], v[26:29]
	v_mfma_f32_16x16x32_f16 v[30:33], v[106:109], v[232:235], v[30:33]
	v_mfma_f32_16x16x32_f16 v[22:25], v[98:101], v[232:235], v[22:25]
	v_mfma_f32_16x16x32_f16 v[18:21], v[90:93], v[232:235], v[18:21]
	s_branch .LBB0_938
; #define MFMA16(a, b, c) __builtin_amdgcn_mfma_f32_16x16x32_f16((a), (b), (c), 0, 0, 0)
; __device__ __forceinline__ float shx(float v, int m) { return __shfl_xor(v, m); }
; template <class KB>
; __device__ __forceinline__ void sel_run(int nit, KB kbof, const half8 (&qf)[2][2], const unsigned char* kf, const unsigned char* vf, const int (&tqs)[2], int qq,
;                                         f32x4 (&o)[2][4], float (&m)[2], float (&l)[2], int g) {
;     ...
; #pragma unroll
;         for (int s_ = 0; s_ < 2; ++s_)
;             if (need[s_]) {
;                 float p[4][4]; float mx = -1e30f;
;                 const int klim = selq[s_] ? tqs[s_] - kbA - 4 * g : -1;
; #pragma unroll
;                 for (int t = 0; t < 4; ++t)
; #pragma unroll
;                     for (int r = 0; r < 4; ++r) { if (16 * t + r <= klim) mx = fmaxf(mx, s[s_][t][r]); }
;                 if (__ballot(mx > m[s_] + RESC_THR) != 0ull) {
;                     mx = fmaxf(mx, shx(mx, 16)); mx = fmaxf(mx, shx(mx, 32));
;                     const float mn = fmaxf(m[s_], mx); const float corr = __builtin_amdgcn_exp2f(m[s_] - mn); m[s_] = mn;
;                     l[s_] = l[s_] * corr;
; #pragma unroll
;                     for (int dt = 0; dt < 4; ++dt) o[s_][dt] = o[s_][dt] * corr;
;                 }
;                 float ps = 0.f;
; #pragma unroll
;                 for (int t = 0; t < 4; ++t)
; #pragma unroll
;                     for (int r = 0; r < 4; ++r) { p[t][r] = (16 * t + r <= klim) ? __builtin_amdgcn_exp2f(s[s_][t][r] - m[s_]) : 0.f; ps += p[t][r]; }
;                 l[s_] = l[s_] + ps;
;                 const half8 pfA = {(half_t)p[0][0], (half_t)p[0][1], (half_t)p[0][2], (half_t)p[0][3], (half_t)p[1][0], (half_t)p[1][1], (half_t)p[1][2], (half_t)p[1][3]};
;                 const half8 pfB = {(half_t)p[2][0], (half_t)p[2][1], (half_t)p[2][2], (half_t)p[2][3], (half_t)p[3][0], (half_t)p[3][1], (half_t)p[3][2], (half_t)p[3][3]};
; #pragma unroll
;                 for (int dt = 0; dt < 4; ++dt) { o[s_][dt] = MFMA16(vh[dt], pfA, o[s_][dt]); o[s_][dt] = MFMA16(vh[4 + dt], pfB, o[s_][dt]); }
;             }
;         kbA = kbN; eA = eN;
.Lsel_fast1:
	v_lshrrev_b32_e64 v227, v214, s33
	v_max3_f32 v228, v50, v51, v52
	v_and_b32_e32 v227, 1, v227
	v_max3_f32 v229, v53, v58, v59
	v_cmp_eq_u32_e64 s[10:11], 1, v227
	v_max3_f32 v230, v60, v61, v66
	v_max3_f32 v231, v67, v68, v69
	v_max3_f32 v228, v228, v74, v75
	v_max3_f32 v229, v229, v76, v77
	v_add_f32_e32 v232, 0x41400000, v151
	v_max3_f32 v228, v228, v230, v231
	v_max_f32_e32 v228, v228, v229
	v_cndmask_b32_e64 v227, v172, v228, s[10:11]
	v_cmp_gt_f32_e32 vcc, v227, v232
	s_cbranch_vccz .Lsel_fast1_go
	ds_bpermute_b32 v228, v173, v227
	v_max_f32_e32 v227, v227, v227
	s_waitcnt lgkmcnt(0)
	v_max_f32_e32 v228, v228, v228
	v_max_f32_e32 v227, v227, v228
	ds_bpermute_b32 v228, v222, v227
	s_waitcnt lgkmcnt(0)
	v_max3_f32 v227, v151, v227, v228
	v_sub_f32_e32 v151, v151, v227
	v_exp_f32_e32 v228, v151
	v_mov_b32_e32 v151, v227
	v_mul_f32_e32 v147, v147, v228
	v_pk_mul_f32 v[14:15], v[14:15], v[228:229] op_sel_hi:[1,0]
	v_pk_mul_f32 v[16:17], v[16:17], v[228:229] op_sel_hi:[1,0]
	v_pk_mul_f32 v[10:11], v[10:11], v[228:229] op_sel_hi:[1,0]
	v_pk_mul_f32 v[12:13], v[12:13], v[228:229] op_sel_hi:[1,0]
	v_pk_mul_f32 v[6:7], v[6:7], v[228:229] op_sel_hi:[1,0]
	v_pk_mul_f32 v[8:9], v[8:9], v[228:229] op_sel_hi:[1,0]
	v_pk_mul_f32 v[2:3], v[2:3], v[228:229] op_sel_hi:[1,0]
	v_pk_mul_f32 v[4:5], v[4:5], v[228:229] op_sel_hi:[1,0]
.Lsel_fast1_go:
	v_cndmask_b32_e64 v227, -v172, v151, s[10:11]
	v_sub_f32_e32 v228, v50, v227
	v_sub_f32_e32 v229, v51, v227
	v_sub_f32_e32 v230, v52, v227
	v_sub_f32_e32 v231, v53, v227
	v_sub_f32_e32 v232, v58, v227
	v_sub_f32_e32 v233, v59, v227
	v_sub_f32_e32 v234, v60, v227
	v_sub_f32_e32 v235, v61, v227
	v_sub_f32_e32 v236, v66, v227
	v_sub_f32_e32 v237, v67, v227
	v_sub_f32_e32 v238, v68, v227
	v_sub_f32_e32 v239, v69, v227
	v_sub_f32_e32 v240, v74, v227
	v_sub_f32_e32 v241, v75, v227
	v_sub_f32_e32 v242, v76, v227
	v_sub_f32_e32 v243, v77, v227
	v_exp_f32_e32 v228, v228
	v_exp_f32_e32 v229, v229
	v_exp_f32_e32 v230, v230
	v_exp_f32_e32 v231, v231
	v_exp_f32_e32 v232, v232
	v_exp_f32_e32 v233, v233
	v_exp_f32_e32 v234, v234
	v_exp_f32_e32 v235, v235
	v_exp_f32_e32 v236, v236
	v_exp_f32_e32 v237, v237
	v_exp_f32_e32 v238, v238
	v_exp_f32_e32 v239, v239
	v_exp_f32_e32 v240, v240
	v_exp_f32_e32 v241, v241
	v_exp_f32_e32 v242, v242
	v_exp_f32_e32 v243, v243
	v_add_f32_e32 v147, v147, v228
	v_add_f32_e32 v227, v229, v230
	v_add_f32_e32 v147, v147, v231
	v_add_f32_e32 v227, v227, v232
	v_add_f32_e32 v147, v147, v233
	v_add_f32_e32 v227, v227, v234
	v_add_f32_e32 v147, v147, v235
	v_add_f32_e32 v227, v227, v236
	v_add_f32_e32 v147, v147, v237
	v_add_f32_e32 v227, v227, v238
	v_add_f32_e32 v147, v147, v239
	v_add_f32_e32 v227, v227, v240
	v_add_f32_e32 v147, v147, v241
	v_add_f32_e32 v227, v227, v242
	v_add_f32_e32 v147, v147, v243
	v_add_f32_e32 v147, v147, v227
	v_cvt_pk_f16_f32 v228, v228, v229
	v_cvt_pk_f16_f32 v229, v230, v231
	v_cvt_pk_f16_f32 v230, v232, v233
	v_cvt_pk_f16_f32 v231, v234, v235
	v_cvt_pk_f16_f32 v232, v236, v237
	v_cvt_pk_f16_f32 v233, v238, v239
	v_cvt_pk_f16_f32 v234, v240, v241
	v_cvt_pk_f16_f32 v235, v242, v243
	v_mfma_f32_16x16x32_f16 v[14:17], v[102:105], v[228:231], v[14:17]
	v_mfma_f32_16x16x32_f16 v[10:13], v[94:97], v[228:231], v[10:13]
	v_mfma_f32_16x16x32_f16 v[6:9], v[86:89], v[228:231], v[6:9]
	v_mfma_f32_16x16x32_f16 v[2:5], v[82:85], v[228:231], v[2:5]
	v_mfma_f32_16x16x32_f16 v[14:17], v[110:113], v[232:235], v[14:17]
	v_mfma_f32_16x16x32_f16 v[10:13], v[106:109], v[232:235], v[10:13]
	v_mfma_f32_16x16x32_f16 v[6:9], v[98:101], v[232:235], v[6:9]
	v_mfma_f32_16x16x32_f16 v[2:5], v[90:93], v[232:235], v[2:5]
	s_branch .LBB0_942

; __global__ void __launch_bounds__(NTHREADS, 2) trunk_fwd(Args a) {
;     extern __shared__ __attribute__((aligned(16))) unsigned char lds[];
	.amdhsa_kernel _Z9trunk_fwd4Args
		.amdhsa_group_segment_fixed_size 0
		.amdhsa_private_segment_fixed_size 0
		.amdhsa_kernarg_size 544
		.amdhsa_user_sgpr_count 2
		.amdhsa_user_sgpr_dispatch_ptr 0
		.amdhsa_user_sgpr_queue_ptr 0
		.amdhsa_user_sgpr_kernarg_segment_ptr 1
		.amdhsa_user_sgpr_dispatch_id 0
		.amdhsa_user_sgpr_kernarg_preload_length 0
		.amdhsa_user_sgpr_kernarg_preload_offset 0
		.amdhsa_user_sgpr_private_segment_size 0
		.amdhsa_uses_dynamic_stack 0
		.amdhsa_enable_private_segment 0
		.amdhsa_system_sgpr_workgroup_id_x 1
		.amdhsa_system_sgpr_workgroup_id_y 0
		.amdhsa_system_sgpr_workgroup_id_z 0
		.amdhsa_system_sgpr_workgroup_info 0
		.amdhsa_system_vgpr_workitem_id 2
		.amdhsa_next_free_vgpr 254
		.amdhsa_next_free_sgpr 102
		.amdhsa_accum_offset 256
		.amdhsa_reserve_vcc 1
		.amdhsa_float_round_mode_32 0
		.amdhsa_float_round_mode_16_64 0
		.amdhsa_float_denorm_mode_32 3
		.amdhsa_float_denorm_mode_16_64 3
		.amdhsa_dx10_clamp 1
		.amdhsa_ieee_mode 1
		.amdhsa_fp16_overflow 0
		.amdhsa_tg_split 0
		.amdhsa_exception_fp_ieee_invalid_op 0
		.amdhsa_exception_fp_denorm_src 0
		.amdhsa_exception_fp_ieee_div_zero 0
		.amdhsa_exception_fp_ieee_overflow 0
		.amdhsa_exception_fp_ieee_underflow 0
		.amdhsa_exception_fp_ieee_inexact 0
		.amdhsa_exception_int_div_zero 0
	.end_amdhsa_kernel

; __global__ void __launch_bounds__(NTHREADS, 2) trunk_fwd(Args a) {
;     extern __shared__ __attribute__((aligned(16))) unsigned char lds[];
amdhsa.kernels:
  - .agpr_count:     0
    .args:
      - .offset:         0
        .size:           288
        .value_kind:     by_value
      - .offset:         288
        .size:           4
        .value_kind:     hidden_block_count_x
      - .offset:         292
        .size:           4
        .value_kind:     hidden_block_count_y
      - .offset:         296
        .size:           4
        .value_kind:     hidden_block_count_z
      - .offset:         300
        .size:           2
        .value_kind:     hidden_group_size_x
      - .offset:         302
        .size:           2
        .value_kind:     hidden_group_size_y
      - .offset:         304
        .size:           2
        .value_kind:     hidden_group_size_z
      - .offset:         306
        .size:           2
        .value_kind:     hidden_remainder_x
      - .offset:         308
        .size:           2
        .value_kind:     hidden_remainder_y
      - .offset:         310
        .size:           2
        .value_kind:     hidden_remainder_z
      - .offset:         328
        .size:           8
        .value_kind:     hidden_global_offset_x
      - .offset:         336
        .size:           8
        .value_kind:     hidden_global_offset_y
      - .offset:         344
        .size:           8
        .value_kind:     hidden_global_offset_z
      - .offset:         352
        .size:           2
        .value_kind:     hidden_grid_dims
      - .offset:         376
        .size:           8
        .value_kind:     hidden_multigrid_sync_arg
      - .offset:         408
        .size:           4
        .value_kind:     hidden_dynamic_lds_size
    .group_segment_fixed_size: 0
    .kernarg_segment_align: 8
    .kernarg_segment_size: 544
    .language:       OpenCL C
    .language_version:
      - 2
      - 0
    .max_flat_workgroup_size: 512
    .name:           _Z9trunk_fwd4Args
    .private_segment_fixed_size: 0
    .sgpr_count:     108
    .sgpr_spill_count: 55
    .symbol:         _Z9trunk_fwd4Args.kd
    .uniform_work_group_size: 1
    .uses_dynamic_stack: false
    .vgpr_count:     254
    .vgpr_spill_count: 0
    .wavefront_size: 64
